# split-K pair rebalanced: K-lo CU takes 36 K-tiles and 96 final-norm rows, partner 28 K-tiles and 160 rows
# baseline (speedup 1.0000x reference)
.Lp9_stage_b:
	s_mov_b32 s100, 10
	s_movk_i32 s91, 32
	s_movk_i32 s97, 33
	s_cmpk_lt_u32 s101, 0x80
	s_cbranch_scc0 .Lp9_hi
	s_mov_b32 s96, 1
	s_add_u32 s4, s78, 0x8000000
	s_addc_u32 s5, s79, 0
	s_add_i32 s98, s101, 0x200
	s_movk_i32 s99, 0x280
	s_branch .Lp9_body
.Lp9_hi:
	s_mov_b32 s96, 2
	s_movk_i32 s91, 24
	s_movk_i32 s97, 25
	s_add_u32 s4, s78, 0x8001200
	s_addc_u32 s5, s79, 0
	s_add_u32 s74, s74, 0x1200
	s_addc_u32 s75, s75, 0
	s_add_i32 s98, s101, 0x180
	s_movk_i32 s99, 0x280
	s_branch .Lp9_body

.Lw10d:
	v_readlane_b32 s2, v254, 6
	v_readlane_b32 s3, v254, 7
	v_and_b32_e32 v0, 63, v210
	v_readfirstlane_b32 s0, v210
	v_lshlrev_b32_e32 v1, 3, v0
	v_lshlrev_b32_e32 v2, 4, v0
	v_mov_b32_e32 v3, 0x3a800000
	v_mov_b32_e32 v121, 0x358637bd
	s_lshr_b32 s0, s0, 6
	global_load_dwordx4 v[4:7], v2, s[2:3]
	global_load_dwordx4 v[8:11], v2, s[2:3] offset:1024
	global_load_dwordx4 v[12:15], v2, s[2:3] offset:2048
	global_load_dwordx4 v[16:19], v2, s[2:3] offset:3072
	s_and_b32 s1, s101, 0x7f
	s_and_b32 s4, s1, 7
	s_lshr_b32 s5, s1, 4
	s_cmp_lt_u32 s4, 4
	s_cselect_b32 s4, 4, 0xff
	s_cmp_eq_u32 s5, s4
	s_cbranch_scc1 .Lp10a_done
	s_and_b32 s4, s1, 7
	s_mul_i32 s4, s4, 20
	s_lshr_b32 s5, s1, 3
	s_add_i32 s4, s4, s5
	s_lshl_b32 s4, s4, 8
	s_cmp_gt_u32 s0, 7
	s_cbranch_scc1 .Lp10a_done
	s_lshr_b32 s11, s101, 7
	s_cmp_eq_u32 s11, 0
	s_cselect_b32 s10, 3, 5
	s_cselect_b32 s11, 0, 0x60
	s_cselect_b32 s5, 12, 20
	s_mul_i32 s5, s5, s0


	s_add_i32 s5, s5, s11
	s_add_i32 s4, s4, s5

	s_lshl_b32 s5, s4, 11
	s_add_u32 s12, s78, s5
	s_addc_u32 s13, s79, 0
	s_add_u32 s12, s12, 0x2000000
	s_addc_u32 s13, s13, 0
	s_lshl_b32 s5, s4, 12
	s_add_u32 s14, s76, s5
	s_addc_u32 s15, s77, 0
